# TG1: non-leader workgroups spin on the cross-XCD release generation directly (one relay hop fewer per full barrier), on top of v066
# speedup vs baseline: 1.0080x; 1.0080x over previous
.LBB0_423:
	s_or_b64 exec, exec, s[28:29]
	v_cvt_f32_u32_e32 v5, v3
	s_waitcnt vmcnt(0)
	v_readfirstlane_b32 s0, v4
	v_sub_u32_e32 v4, 0, v3
	v_rcp_iflag_f32_e32 v5, v5
	v_add_u32_e32 v6, s0, v1
	v_mul_f32_e32 v5, 0x4f7ffffe, v5
	v_cvt_u32_f32_e32 v5, v5
	v_mul_lo_u32 v1, v4, v5
	v_mul_hi_u32 v1, v5, v1
	v_add_u32_e32 v1, v5, v1
	v_mul_hi_u32 v1, v6, v1
	v_mul_lo_u32 v4, v1, v3
	v_sub_u32_e32 v4, v6, v4
	v_add_u32_e32 v5, 1, v1
	v_cmp_ge_u32_e32 vcc, v4, v3
	s_nop 1
	v_cndmask_b32_e32 v1, v1, v5, vcc
	v_sub_u32_e32 v5, v4, v3
	v_cndmask_b32_e32 v4, v4, v5, vcc
	v_add_u32_e32 v5, 1, v1
	v_cmp_ge_u32_e32 vcc, v4, v3
	v_add_u32_e32 v4, 1, v6
	s_nop 0
	v_cndmask_b32_e32 v1, v1, v5, vcc
	v_mul_lo_u32 v5, v3, v1
	v_add_u32_e32 v3, v5, v3
	v_cmp_ne_u32_e32 vcc, v4, v3
	s_and_saveexec_b64 s[0:1], vcc
	s_xor_b64 s[28:29], exec, s[0:1]
	s_cbranch_execz .LBB0_437
	v_readlane_b32 s0, v248, 44
	v_readlane_b32 s1, v248, 45
	s_waitcnt lgkmcnt(0)
	s_nop 3
	global_load_dword v2, v0, s[0:1] sc1
	s_waitcnt vmcnt(0)
	v_cmp_eq_u32_e32 vcc, v2, v1
	s_and_saveexec_b64 s[34:35], vcc
	s_cbranch_execz .LBB0_436
	s_mov_b32 s0, 1
	s_mov_b64 s[38:39], 0
	s_branch .LBB0_427
